# v6 + attention steady-state loop: running row max folded into the QK^T accumulator seed (SrcC = -mhat block), 33 VALU subs per tile removed
# speedup vs baseline: 1.0164x; 1.0041x over previous
.LBB0_1307:
	v_exp_f32_e32 v66, v2
	v_lshlrev_b32_e32 v2, 1, v235
	s_and_b32 s23, s89, 0x3fffffc0
	v_and_b32_e32 v241, 32, v2
	v_lshlrev_b32_e32 v2, 4, v218
	v_exp_f32_e32 v82, v38
	v_exp_f32_e32 v83, v18
	v_exp_f32_e32 v84, v19
	v_exp_f32_e32 v85, v20
	v_exp_f32_e32 v86, v21
	v_exp_f32_e32 v87, v22
	v_exp_f32_e32 v88, v23
	v_exp_f32_e32 v89, v24
	v_exp_f32_e32 v90, v25
	v_exp_f32_e32 v91, v26
	v_exp_f32_e32 v92, v27
	v_exp_f32_e32 v93, v28
	v_exp_f32_e32 v94, v29
	v_exp_f32_e32 v95, v30
	v_exp_f32_e32 v96, v31
	v_exp_f32_e32 v97, v32
	v_exp_f32_e32 v67, v3
	v_exp_f32_e32 v68, v4
	v_exp_f32_e32 v69, v5
	v_exp_f32_e32 v70, v6
	v_exp_f32_e32 v71, v7
	v_exp_f32_e32 v72, v8
	v_exp_f32_e32 v73, v9
	v_exp_f32_e32 v74, v10
	v_exp_f32_e32 v75, v11
	v_exp_f32_e32 v76, v12
	v_exp_f32_e32 v77, v13
	v_exp_f32_e32 v78, v14
	v_exp_f32_e32 v79, v15
	v_exp_f32_e32 v80, v16
	v_exp_f32_e32 v81, v17
	s_lshl_b32 s23, s23, 2
	v_and_b32_e32 v2, 0xc0, v2
	s_lshl_b32 s27, s27, 7
	s_add_i32 s23, s23, 0
	v_lshl_or_b32 v242, v238, 8, v2
	v_add_u32_e32 v2, 0, v241
	s_add_i32 s26, s90, 0x80
	s_add_i32 s40, s50, s27
	s_add_i32 s23, s23, 0x18000
	v_add3_u32 v246, v2, v237, v242
	s_lshr_b32 s26, s26, 6
	s_lshl_b64 s[52:53], s[40:41], 1
	v_and_b32_e32 v2, 3, v218
	s_mov_b32 s36, 1
	s_cmp_lt_u32 s88, 2
	v_cmp_gt_u32_e64 s[38:39], 32, v235
	v_lshl_add_u32 v239, v234, 2, s23
	v_lshlrev_b32_e32 v252, 4, v238
	v_lshlrev_b32_e32 v212, 4, v2
	s_cbranch_scc1 .LBB0_1323
	s_lshl_b64 s[30:31], s[46:47], 1
	s_add_u32 s30, s82, s30
	s_addc_u32 s31, s83, s31
	s_lshl_b32 s27, s89, 10
	v_mov_b32_e32 v213, v195
	s_and_b32 s27, s27, 0x30000
	v_lshl_add_u64 v[2:3], s[0:1], 1, v[212:213]
	v_lshl_or_b32 v4, v219, 12, s27
	v_mov_b32_e32 v5, v195
	v_lshl_add_u64 v[2:3], v[2:3], 0, v[4:5]
	v_mov_b32_e32 v18, v195
	v_mov_b32_e32 v19, v195
	v_mov_b32_e32 v32, v195
	v_mov_b32_e32 v33, v195
	v_lshl_add_u64 v[216:217], s[82:83], 0, v[2:3]
	v_mov_b32_e32 v20, v195
	v_mov_b32_e32 v21, v195
	v_mov_b32_e32 v22, v195
	v_mov_b32_e32 v23, v195
	v_mov_b32_e32 v24, v195
	v_mov_b32_e32 v25, v195
	v_mov_b32_e32 v26, v195
	v_mov_b32_e32 v27, v195
	v_mov_b32_e32 v28, v195
	v_mov_b32_e32 v29, v195
	v_mov_b32_e32 v30, v195
	v_mov_b32_e32 v31, v195
	v_mov_b64_e32 v[64:65], v[32:33]
	v_mov_b64_e32 v[48:49], v[32:33]
	v_mov_b64_e32 v[2:3], v[18:19]
	s_mov_b32 s28, 4
	v_lshl_add_u64 v[214:215], s[30:31], 0, v[194:195]
	s_mov_b32 s30, 0
	s_mov_b32 s29, 0x8000
	s_movk_i32 s91, 0x4000
	v_mov_b32_e32 v250, 0
	v_add_u32_e32 v213, s23, v252
	v_mov_b64_e32 v[62:63], v[30:31]
	v_mov_b64_e32 v[60:61], v[28:29]
	v_mov_b64_e32 v[58:59], v[26:27]
	v_mov_b64_e32 v[56:57], v[24:25]
	v_mov_b64_e32 v[54:55], v[22:23]
	v_mov_b64_e32 v[52:53], v[20:21]
	v_mov_b64_e32 v[50:51], v[18:19]
	v_mov_b64_e32 v[46:47], v[30:31]
	v_mov_b64_e32 v[44:45], v[28:29]
	v_mov_b64_e32 v[42:43], v[26:27]
	v_mov_b64_e32 v[40:41], v[24:25]
	v_mov_b64_e32 v[38:39], v[22:23]
	v_mov_b64_e32 v[36:37], v[20:21]
	v_mov_b64_e32 v[34:35], v[18:19]
	v_mov_b64_e32 v[4:5], v[20:21]
	v_mov_b64_e32 v[6:7], v[22:23]
	v_mov_b64_e32 v[8:9], v[24:25]
	v_mov_b64_e32 v[10:11], v[26:27]
	v_mov_b64_e32 v[12:13], v[28:29]
	v_mov_b64_e32 v[14:15], v[30:31]
	v_mov_b64_e32 v[16:17], v[32:33]
	v_lshl_add_u32 v114, v235, 4, s14
	v_add_u32_e32 v114, 0x1ca00, v114
	ds_write_b128 v114, v[218:221]
	ds_write_b128 v114, v[222:225] offset:1024
	ds_write_b128 v114, v[226:229] offset:2048
	ds_write_b128 v114, v[230:233] offset:3072
	s_nop 3
	v_sub_f32_e32 v218, 0, v243
	v_sub_f32_e32 v219, 0, v243
	v_sub_f32_e32 v220, 0, v243
	v_sub_f32_e32 v221, 0, v243
	v_sub_f32_e32 v222, 0, v243
	v_sub_f32_e32 v223, 0, v243
	v_sub_f32_e32 v224, 0, v243
	v_sub_f32_e32 v225, 0, v243
	v_sub_f32_e32 v226, 0, v243
	v_sub_f32_e32 v227, 0, v243
	v_sub_f32_e32 v228, 0, v243
	v_sub_f32_e32 v229, 0, v243
	v_sub_f32_e32 v230, 0, v243
	v_sub_f32_e32 v231, 0, v243
	v_sub_f32_e32 v232, 0, v243
	v_sub_f32_e32 v233, 0, v243
	s_nop 1
.LBB0_1309:
	s_waitcnt lgkmcnt(7)
	v_mfma_f32_32x32x16_bf16 v[114:129], v[190:193], v[150:153], v[218:233]
	v_add_f32_e32 v98, v82, v83
	v_add_f32_e32 v98, v84, v98
	v_add_f32_e32 v98, v85, v98
	v_add_f32_e32 v98, v86, v98
	v_add_u32_e32 v247, s30, v246
	v_add_f32_e32 v98, v87, v98
	v_cvt_pk_bf16_f32 v158, v82, v83
	v_cvt_pk_bf16_f32 v159, v84, v85
	s_nop 0
	v_add_f32_e32 v82, v88, v98
	s_waitcnt lgkmcnt(6)
	v_mfma_f32_32x32x16_bf16 v[98:113], v[182:185], v[150:153], v[218:233]
	v_add_f32_e32 v82, v89, v82
	v_add_f32_e32 v82, v90, v82
	v_add_f32_e32 v82, v91, v82
	v_cvt_pk_bf16_f32 v160, v86, v87
	v_cvt_pk_bf16_f32 v161, v88, v89
	s_waitcnt lgkmcnt(5)
	v_mfma_f32_32x32x16_bf16 v[114:129], v[186:189], v[146:149], v[114:129]
	v_add_f32_e32 v82, v92, v82
	v_add_f32_e32 v82, v93, v82
	v_add_f32_e32 v82, v94, v82
	v_add_f32_e32 v82, v95, v82
	v_cvt_pk_bf16_f32 v154, v90, v91
	v_cvt_pk_bf16_f32 v155, v92, v93
	s_waitcnt lgkmcnt(4)
	v_mfma_f32_32x32x16_bf16 v[98:113], v[178:181], v[146:149], v[98:113]
	v_add_f32_e32 v82, v96, v82
	v_add_f32_e32 v82, v97, v82
	v_add_f32_e32 v82, v66, v82
	v_add_f32_e32 v86, v67, v82
	v_cvt_pk_bf16_f32 v156, v94, v95
	v_cvt_pk_bf16_f32 v157, v96, v97
	ds_read_b64_tr_b16 v[82:83], v247 offset:49152
	ds_read_b64_tr_b16 v[84:85], v247 offset:49664
	s_waitcnt lgkmcnt(5)
	v_mfma_f32_32x32x16_bf16 v[114:129], v[174:177], v[142:145], v[114:129]
	v_add_f32_e32 v86, v68, v86
	v_add_f32_e32 v86, v69, v86
	v_add_f32_e32 v86, v70, v86
	v_add_f32_e32 v86, v71, v86
	v_cvt_pk_bf16_f32 v138, v66, v67
	v_cvt_pk_bf16_f32 v139, v68, v69
	ds_read_b64_tr_b16 v[66:67], v247 offset:50176
	ds_read_b64_tr_b16 v[68:69], v247 offset:50688
	s_waitcnt lgkmcnt(6)
	v_mfma_f32_32x32x16_bf16 v[98:113], v[170:173], v[142:145], v[98:113]
	v_add_f32_e32 v86, v72, v86
	v_add_f32_e32 v86, v73, v86
	v_add_f32_e32 v86, v74, v86
	v_add_f32_e32 v86, v75, v86
	v_cvt_pk_bf16_f32 v140, v70, v71
	v_cvt_pk_bf16_f32 v141, v72, v73
	ds_read_b64_tr_b16 v[70:71], v247 offset:53248
	ds_read_b64_tr_b16 v[72:73], v247 offset:53760
	s_waitcnt lgkmcnt(7)
	v_mfma_f32_32x32x16_bf16 v[114:129], v[166:169], v[134:137], v[114:129]
	v_add_f32_e32 v86, v76, v86
	v_add_f32_e32 v86, v77, v86
	v_add_f32_e32 v86, v78, v86
	v_add_f32_e32 v86, v79, v86
	v_cvt_pk_bf16_f32 v130, v74, v75
	v_cvt_pk_bf16_f32 v131, v76, v77
	ds_read_b64_tr_b16 v[74:75], v247 offset:54272
	ds_read_b64_tr_b16 v[76:77], v247 offset:54784
	s_waitcnt lgkmcnt(8)
	v_mfma_f32_32x32x16_bf16 v[98:113], v[162:165], v[134:137], v[98:113]
	v_add_f32_e32 v86, v80, v86
	v_add_f32_e32 v86, v81, v86
	v_add_f32_e32 v86, 0, v86
	v_cvt_pk_bf16_f32 v132, v78, v79
	v_cvt_pk_bf16_f32 v133, v80, v81
	v_lshl_add_u64 v[188:189], v[214:215], 0, s[52:53]
	v_lshl_add_u64 v[78:79], v[188:189], 0, s[70:71]
	s_add_i32 s27, s91, s25
	s_mov_b32 s30, m0
	s_mov_b32 m0, s27
	s_nop 0
	global_load_lds_dwordx4 v[78:79], off
	s_mov_b32 m0, s30
	v_lshl_add_u64 v[78:79], v[188:189], 0, s[72:73]
	v_lshl_add_u64 v[186:187], v[216:217], 0, s[52:53]
	s_addk_i32 s27, 0x2000
	s_mov_b32 s30, m0
	s_mov_b32 m0, s27
	s_nop 0
	global_load_lds_dwordx4 v[78:79], off
	s_mov_b32 m0, s30
	v_lshl_add_u64 v[78:79], v[186:187], 0, s[74:75]
	s_add_i32 s27, s29, s24
	s_mov_b32 s30, m0
	s_mov_b32 m0, s27
	s_nop 0
	global_load_lds_dwordx4 v[78:79], off
	s_mov_b32 m0, s30
	v_lshl_add_u64 v[78:79], v[186:187], 0, s[76:77]
	s_addk_i32 s27, 0x2000
	s_mov_b32 s30, m0
	s_mov_b32 m0, s27
	s_nop 0
	global_load_lds_dwordx4 v[78:79], off
	s_mov_b32 m0, s30
	v_max_f32_e32 v78, v115, v115
	v_max_f32_e32 v79, v114, v114
	v_max_f32_e32 v78, v79, v78
	v_max3_f32 v79, v116, v117, v99
	v_max3_f32 v78, v78, v98, v100
	v_max3_f32 v78, v78, v101, v118
	v_max3_f32 v79, v79, v120, v121
	v_max3_f32 v78, v78, v119, v102
	v_max3_f32 v79, v79, v104, v105
	v_max3_f32 v78, v78, v103, v122
	v_max3_f32 v79, v79, v124, v125
	v_max3_f32 v78, v78, v123, v106
	v_max3_f32 v79, v79, v108, v109
	v_max3_f32 v78, v78, v107, v126
	v_max3_f32 v79, v79, v128, v129
	v_max3_f32 v78, v78, v127, v110
	v_max3_f32 v79, v79, v112, v113
	v_max3_f32 v78, v78, v111, v79
	v_mov_b32_e32 v79, v78
	s_nop 1
	v_permlane32_swap_b32_e32 v78, v79
	v_max_f32_e32 v79, v79, v79
	v_max_f32_e32 v78, v78, v78
	v_max_f32_e32 v78, v78, v79
	v_cmp_lt_f32_e32 vcc, s93, v78
	s_cmp_lg_u64 vcc, 0
	v_add_f32_e32 v190, v250, v86
	s_cselect_b64 s[36:37], -1, 0
	s_cbranch_vccnz .LBB0_1317
.LBB0_1310:
	s_waitcnt lgkmcnt(6)
	v_mfma_f32_32x32x16_bf16 v[18:33], v[158:161], v[82:85], v[18:33]
	v_exp_f32_e32 v114, v114
	v_exp_f32_e32 v115, v115
	ds_read_b64_tr_b16 v[78:79], v247 offset:57344
	ds_read_b64_tr_b16 v[80:81], v247 offset:57856
	s_waitcnt lgkmcnt(6)
	v_mfma_f32_32x32x16_bf16 v[18:33], v[154:157], v[66:69], v[18:33]
	v_exp_f32_e32 v116, v116
	v_exp_f32_e32 v117, v117
	ds_read_b64_tr_b16 v[66:67], v247 offset:58368
	ds_read_b64_tr_b16 v[68:69], v247 offset:58880
	s_waitcnt lgkmcnt(6)
	v_mfma_f32_32x32x16_bf16 v[50:65], v[158:161], v[70:73], v[50:65]
	v_exp_f32_e32 v118, v118
	v_exp_f32_e32 v119, v119
	ds_read_b64_tr_b16 v[70:71], v247 offset:61440
	ds_read_b64_tr_b16 v[72:73], v247 offset:61952
	s_waitcnt lgkmcnt(6)
	v_mfma_f32_32x32x16_bf16 v[50:65], v[154:157], v[74:77], v[50:65]
	v_exp_f32_e32 v120, v120
	v_exp_f32_e32 v121, v121
	ds_read_b64_tr_b16 v[74:75], v247 offset:62464
	ds_read_b64_tr_b16 v[76:77], v247 offset:62976
	s_waitcnt lgkmcnt(6)
	v_mfma_f32_32x32x16_bf16 v[34:49], v[158:161], v[78:81], v[34:49]
	v_exp_f32_e32 v122, v122
	v_exp_f32_e32 v123, v123
	ds_read_b64_tr_b16 v[78:79], v247 offset:51200
	ds_read_b64_tr_b16 v[80:81], v247 offset:51712
	s_waitcnt lgkmcnt(6)
	v_mfma_f32_32x32x16_bf16 v[34:49], v[154:157], v[66:69], v[34:49]
	v_exp_f32_e32 v124, v124
	v_exp_f32_e32 v125, v125
	ds_read_b64_tr_b16 v[82:83], v247 offset:52224
	ds_read_b64_tr_b16 v[84:85], v247 offset:52736
	s_waitcnt lgkmcnt(6)
	v_mfma_f32_32x32x16_bf16 v[2:17], v[158:161], v[70:73], v[2:17]
	v_exp_f32_e32 v126, v126
	v_exp_f32_e32 v127, v127
	ds_read_b64_tr_b16 v[86:87], v247 offset:55296
	ds_read_b64_tr_b16 v[88:89], v247 offset:55808
	s_waitcnt lgkmcnt(6)
	v_mfma_f32_32x32x16_bf16 v[2:17], v[154:157], v[74:77], v[2:17]
	v_exp_f32_e32 v128, v128
	v_exp_f32_e32 v129, v129
	ds_read_b64_tr_b16 v[74:75], v247 offset:56320
	ds_read_b64_tr_b16 v[76:77], v247 offset:56832
	v_add_u32_e32 v90, s29, v245
	ds_read_b128 v[70:73], v90
	ds_read_b128 v[66:69], v90 offset:512
	s_waitcnt lgkmcnt(8)
	v_mfma_f32_32x32x16_bf16 v[18:33], v[138:141], v[78:81], v[18:33]
	v_exp_f32_e32 v98, v98
	v_exp_f32_e32 v99, v99
	ds_read_b64_tr_b16 v[78:79], v247 offset:59392
	ds_read_b64_tr_b16 v[80:81], v247 offset:59904
	ds_read_b128 v[182:185], v90 offset:2048
	ds_read_b128 v[174:177], v90 offset:2560
	s_waitcnt lgkmcnt(10)
	v_mfma_f32_32x32x16_bf16 v[18:33], v[130:133], v[82:85], v[18:33]
	v_exp_f32_e32 v100, v100
	v_exp_f32_e32 v101, v101
	ds_read_b64_tr_b16 v[82:83], v247 offset:60416
	ds_read_b64_tr_b16 v[84:85], v247 offset:60928
	ds_read_b128 v[178:181], v90 offset:4096
	ds_read_b128 v[166:169], v90 offset:4608
	s_waitcnt lgkmcnt(12)
	v_mfma_f32_32x32x16_bf16 v[50:65], v[138:141], v[86:89], v[50:65]
	v_exp_f32_e32 v102, v102
	v_exp_f32_e32 v103, v103
	ds_read_b64_tr_b16 v[86:87], v247 offset:63488
	ds_read_b64_tr_b16 v[88:89], v247 offset:64000
	ds_read_b128 v[170:173], v90 offset:6144
	ds_read_b128 v[162:165], v90 offset:6656
	s_waitcnt lgkmcnt(14)
	v_mfma_f32_32x32x16_bf16 v[50:65], v[130:133], v[74:77], v[50:65]
	v_exp_f32_e32 v104, v104
	v_exp_f32_e32 v105, v105
	ds_read_b64_tr_b16 v[74:75], v247 offset:64512
	ds_read_b64_tr_b16 v[76:77], v247 offset:65024
	s_waitcnt lgkmcnt(12)
	v_mfma_f32_32x32x16_bf16 v[34:49], v[138:141], v[78:81], v[34:49]
	v_exp_f32_e32 v106, v106
	v_exp_f32_e32 v107, v107
	s_waitcnt lgkmcnt(8)
	v_mfma_f32_32x32x16_bf16 v[34:49], v[130:133], v[82:85], v[34:49]
	v_exp_f32_e32 v108, v108
	v_exp_f32_e32 v109, v109
	s_waitcnt lgkmcnt(4)
	v_mfma_f32_32x32x16_bf16 v[2:17], v[138:141], v[86:89], v[2:17]
	v_exp_f32_e32 v110, v110
	v_exp_f32_e32 v111, v111
	s_waitcnt lgkmcnt(0)
	v_mfma_f32_32x32x16_bf16 v[2:17], v[130:133], v[74:77], v[2:17]
	v_exp_f32_e32 v112, v112
	v_exp_f32_e32 v113, v113
	s_waitcnt vmcnt(4) lgkmcnt(0)
	s_barrier
	s_andn2_b64 vcc, exec, s[36:37]
	s_cbranch_vccnz .LBB0_1312
	s_waitcnt lgkmcnt(0)
	ds_read_b128 v[74:77], v213 offset:96
	ds_read_b128 v[78:81], v213 offset:64
	ds_read_b128 v[82:85], v213 offset:32
	ds_read_b128 v[86:89], v213
	s_waitcnt lgkmcnt(3)
	v_pk_mul_f32 v[30:31], v[30:31], v[74:75]
	s_waitcnt lgkmcnt(2)
	v_pk_mul_f32 v[26:27], v[26:27], v[78:79]
	s_waitcnt lgkmcnt(1)
	v_pk_mul_f32 v[22:23], v[22:23], v[82:83]
	v_pk_mul_f32 v[32:33], v[32:33], v[76:77]
	v_pk_mul_f32 v[28:29], v[28:29], v[80:81]
	v_pk_mul_f32 v[24:25], v[24:25], v[84:85]
	s_waitcnt lgkmcnt(0)
	v_pk_mul_f32 v[20:21], v[20:21], v[88:89]
	v_pk_mul_f32 v[18:19], v[18:19], v[86:87]
	v_pk_mul_f32 v[62:63], v[62:63], v[74:75]
	v_pk_mul_f32 v[58:59], v[58:59], v[78:79]
	v_pk_mul_f32 v[54:55], v[54:55], v[82:83]
	v_pk_mul_f32 v[64:65], v[64:65], v[76:77]
	v_pk_mul_f32 v[60:61], v[60:61], v[80:81]
	v_pk_mul_f32 v[56:57], v[56:57], v[84:85]
	v_pk_mul_f32 v[52:53], v[52:53], v[88:89]
	v_pk_mul_f32 v[50:51], v[50:51], v[86:87]
	v_pk_mul_f32 v[46:47], v[46:47], v[74:75]
	v_pk_mul_f32 v[42:43], v[42:43], v[78:79]
	v_pk_mul_f32 v[38:39], v[38:39], v[82:83]
	v_pk_mul_f32 v[48:49], v[48:49], v[76:77]
	v_pk_mul_f32 v[44:45], v[44:45], v[80:81]
	v_pk_mul_f32 v[40:41], v[40:41], v[84:85]
	v_pk_mul_f32 v[36:37], v[36:37], v[88:89]
	v_pk_mul_f32 v[34:35], v[34:35], v[86:87]
	v_pk_mul_f32 v[14:15], v[14:15], v[74:75]
	v_pk_mul_f32 v[10:11], v[10:11], v[78:79]
	v_pk_mul_f32 v[6:7], v[6:7], v[82:83]
	v_pk_mul_f32 v[16:17], v[16:17], v[76:77]
	v_pk_mul_f32 v[12:13], v[12:13], v[80:81]
	v_pk_mul_f32 v[8:9], v[8:9], v[84:85]
	v_pk_mul_f32 v[4:5], v[4:5], v[88:89]
	v_pk_mul_f32 v[2:3], v[2:3], v[86:87]
.LBB0_1312:
	s_add_i32 s27, s29, 0x4000
	s_cmpk_lg_u32 s29, 0x8000
	s_cselect_b32 s27, s27, 0
	v_mfma_f32_32x32x16_bf16 v[82:97], v[70:73], v[150:153], v[218:233]
	v_add_f32_e32 v74, v114, v115
	v_add_f32_e32 v74, v116, v74
	v_add_f32_e32 v74, v117, v74
	v_add_f32_e32 v74, v118, v74
	v_add_u32_e32 v247, s91, v246
	v_add_f32_e32 v74, v119, v74
	v_cvt_pk_bf16_f32 v158, v114, v115
	v_cvt_pk_bf16_f32 v159, v116, v117
	s_nop 0
	v_add_f32_e32 v70, v120, v74
	v_add_f32_e32 v70, v121, v70
	v_add_f32_e32 v70, v122, v70
	v_add_f32_e32 v114, v123, v70
	v_mfma_f32_32x32x16_bf16 v[66:81], v[66:69], v[150:153], v[218:233]
	v_cvt_pk_bf16_f32 v160, v118, v119
	v_cvt_pk_bf16_f32 v161, v120, v121
	v_mfma_f32_32x32x16_bf16 v[82:97], v[182:185], v[146:149], v[82:97]
	v_add_f32_e32 v114, v124, v114
	v_add_f32_e32 v114, v125, v114
	v_add_f32_e32 v114, v126, v114
	v_add_f32_e32 v114, v127, v114
	v_cvt_pk_bf16_f32 v154, v122, v123
	v_cvt_pk_bf16_f32 v155, v124, v125
	v_mfma_f32_32x32x16_bf16 v[66:81], v[174:177], v[146:149], v[66:81]
	v_add_f32_e32 v114, v128, v114
	v_add_f32_e32 v114, v129, v114
	v_add_f32_e32 v114, v98, v114
	v_add_f32_e32 v118, v99, v114
	v_cvt_pk_bf16_f32 v156, v126, v127
	v_cvt_pk_bf16_f32 v157, v128, v129
	ds_read_b64_tr_b16 v[114:115], v247 offset:49152
	ds_read_b64_tr_b16 v[116:117], v247 offset:49664
	v_mfma_f32_32x32x16_bf16 v[82:97], v[178:181], v[142:145], v[82:97]
	v_add_f32_e32 v118, v100, v118
	v_add_f32_e32 v118, v101, v118
	v_add_f32_e32 v118, v102, v118
	v_add_f32_e32 v118, v103, v118
	v_cvt_pk_bf16_f32 v138, v98, v99
	v_cvt_pk_bf16_f32 v139, v100, v101
	ds_read_b64_tr_b16 v[98:99], v247 offset:50176
	ds_read_b64_tr_b16 v[100:101], v247 offset:50688
	v_mfma_f32_32x32x16_bf16 v[66:81], v[166:169], v[142:145], v[66:81]
	v_add_f32_e32 v118, v104, v118
	v_add_f32_e32 v118, v105, v118
	v_add_f32_e32 v118, v106, v118
	v_add_f32_e32 v118, v107, v118
	v_cvt_pk_bf16_f32 v140, v102, v103
	v_cvt_pk_bf16_f32 v141, v104, v105
	ds_read_b64_tr_b16 v[102:103], v247 offset:53248
	ds_read_b64_tr_b16 v[104:105], v247 offset:53760
	v_mfma_f32_32x32x16_bf16 v[82:97], v[170:173], v[134:137], v[82:97]
	v_add_f32_e32 v118, v108, v118
	v_add_f32_e32 v118, v109, v118
	v_add_f32_e32 v118, v110, v118
	v_add_f32_e32 v118, v111, v118
	v_cvt_pk_bf16_f32 v130, v106, v107
	v_cvt_pk_bf16_f32 v131, v108, v109
	ds_read_b64_tr_b16 v[106:107], v247 offset:54272
	ds_read_b64_tr_b16 v[108:109], v247 offset:54784
	v_mfma_f32_32x32x16_bf16 v[66:81], v[162:165], v[134:137], v[66:81]
	v_add_f32_e32 v118, v112, v118
	v_add_f32_e32 v118, v113, v118
	v_add_f32_e32 v118, 0, v118
	v_cvt_pk_bf16_f32 v132, v110, v111
	v_cvt_pk_bf16_f32 v133, v112, v113
	s_mov_b64 s[30:31], 0x1dd40000
	v_lshl_add_u64 v[110:111], v[188:189], 0, s[30:31]
	s_add_i32 s36, s29, s25
	s_mov_b32 s30, m0
	s_mov_b32 m0, s36
	s_nop 0
	global_load_lds_dwordx4 v[110:111], off
	s_mov_b32 m0, s30
	s_mov_b64 s[30:31], 0x1dd40080
	v_lshl_add_u64 v[110:111], v[188:189], 0, s[30:31]
	s_add_i32 s30, s36, 0x2000
	s_mov_b32 s31, m0
	s_mov_b32 m0, s30
	s_nop 0
	global_load_lds_dwordx4 v[110:111], off
	s_mov_b32 m0, s31
	s_mov_b64 s[30:31], 0x25cc0000
	v_lshl_add_u64 v[110:111], v[186:187], 0, s[30:31]
	s_add_i32 s36, s27, s24
	s_mov_b32 s30, m0
	s_mov_b32 m0, s36
	s_nop 0
	global_load_lds_dwordx4 v[110:111], off
	s_mov_b32 m0, s30
	s_mov_b64 s[30:31], 0x25cc0080
	v_lshl_add_u64 v[110:111], v[186:187], 0, s[30:31]
	s_add_i32 s30, s36, 0x2000
	s_mov_b32 s31, m0
	s_mov_b32 m0, s30
	s_nop 0
	global_load_lds_dwordx4 v[110:111], off
	s_mov_b32 m0, s31
	v_max_f32_e32 v110, v83, v83
	v_max_f32_e32 v111, v82, v82
	v_max_f32_e32 v110, v111, v110
	v_max3_f32 v111, v84, v85, v67
	v_max3_f32 v110, v110, v66, v68
	v_max3_f32 v110, v110, v69, v86
	v_max3_f32 v111, v111, v88, v89
	v_max3_f32 v110, v110, v87, v70
	v_max3_f32 v111, v111, v72, v73
	v_max3_f32 v110, v110, v71, v90
	v_max3_f32 v111, v111, v92, v93
	v_max3_f32 v110, v110, v91, v74
	v_max3_f32 v111, v111, v76, v77
	v_max3_f32 v110, v110, v75, v94
	v_max3_f32 v111, v111, v96, v97
	v_max3_f32 v110, v110, v95, v78
	v_max3_f32 v111, v111, v80, v81
	v_max3_f32 v110, v110, v79, v111
	v_mov_b32_e32 v111, v110
	s_nop 1
	v_permlane32_swap_b32_e32 v110, v111
	v_max_f32_e32 v111, v111, v111
	v_max_f32_e32 v110, v110, v110
	v_max_f32_e32 v110, v110, v111
	v_cmp_lt_f32_e32 vcc, s93, v110
	s_cmp_lg_u64 vcc, 0
	v_add_f32_e32 v250, v190, v118
	s_cselect_b64 s[36:37], -1, 0
	s_cbranch_vccnz .LBB0_1320
.LBB0_1313:
	s_waitcnt lgkmcnt(6)
	v_mfma_f32_32x32x16_bf16 v[18:33], v[158:161], v[114:117], v[18:33]
	v_exp_f32_e32 v82, v82
	v_exp_f32_e32 v83, v83
	ds_read_b64_tr_b16 v[110:111], v247 offset:57344
	ds_read_b64_tr_b16 v[112:113], v247 offset:57856
	s_waitcnt lgkmcnt(6)
	v_mfma_f32_32x32x16_bf16 v[18:33], v[154:157], v[98:101], v[18:33]
	v_exp_f32_e32 v84, v84
	v_exp_f32_e32 v85, v85
	ds_read_b64_tr_b16 v[98:99], v247 offset:58368
	ds_read_b64_tr_b16 v[100:101], v247 offset:58880
	s_waitcnt lgkmcnt(6)
	v_mfma_f32_32x32x16_bf16 v[50:65], v[158:161], v[102:105], v[50:65]
	v_exp_f32_e32 v86, v86
	v_exp_f32_e32 v87, v87
	ds_read_b64_tr_b16 v[102:103], v247 offset:61440
	ds_read_b64_tr_b16 v[104:105], v247 offset:61952
	s_waitcnt lgkmcnt(6)
	v_mfma_f32_32x32x16_bf16 v[50:65], v[154:157], v[106:109], v[50:65]
	v_exp_f32_e32 v88, v88
	v_exp_f32_e32 v89, v89
	ds_read_b64_tr_b16 v[106:107], v247 offset:62464
	ds_read_b64_tr_b16 v[108:109], v247 offset:62976
	s_waitcnt lgkmcnt(6)
	v_mfma_f32_32x32x16_bf16 v[34:49], v[158:161], v[110:113], v[34:49]
	v_exp_f32_e32 v90, v90
	v_exp_f32_e32 v91, v91
	ds_read_b64_tr_b16 v[110:111], v247 offset:51200
	ds_read_b64_tr_b16 v[112:113], v247 offset:51712
	s_waitcnt lgkmcnt(6)
	v_mfma_f32_32x32x16_bf16 v[34:49], v[154:157], v[98:101], v[34:49]
	v_exp_f32_e32 v92, v92
	v_exp_f32_e32 v93, v93
	ds_read_b64_tr_b16 v[98:99], v247 offset:52224
	ds_read_b64_tr_b16 v[100:101], v247 offset:52736
	s_waitcnt lgkmcnt(6)
	v_mfma_f32_32x32x16_bf16 v[2:17], v[158:161], v[102:105], v[2:17]
	v_exp_f32_e32 v94, v94
	v_exp_f32_e32 v95, v95
	ds_read_b64_tr_b16 v[102:103], v247 offset:55296
	ds_read_b64_tr_b16 v[104:105], v247 offset:55808
	s_waitcnt lgkmcnt(6)
	v_mfma_f32_32x32x16_bf16 v[2:17], v[154:157], v[106:109], v[2:17]
	v_exp_f32_e32 v96, v96
	v_exp_f32_e32 v97, v97
	ds_read_b64_tr_b16 v[106:107], v247 offset:56320
	ds_read_b64_tr_b16 v[108:109], v247 offset:56832
	v_add_u32_e32 v114, s27, v245
	ds_read_b128 v[190:193], v114
	ds_read_b128 v[182:185], v114 offset:512
	s_waitcnt lgkmcnt(8)
	v_mfma_f32_32x32x16_bf16 v[18:33], v[138:141], v[110:113], v[18:33]
	v_exp_f32_e32 v66, v66
	v_exp_f32_e32 v67, v67
	ds_read_b64_tr_b16 v[110:111], v247 offset:59392
	ds_read_b64_tr_b16 v[112:113], v247 offset:59904
	ds_read_b128 v[186:189], v114 offset:2048
	ds_read_b128 v[178:181], v114 offset:2560
	s_waitcnt lgkmcnt(10)
	v_mfma_f32_32x32x16_bf16 v[18:33], v[130:133], v[98:101], v[18:33]
	v_exp_f32_e32 v68, v68
	v_exp_f32_e32 v69, v69
	ds_read_b64_tr_b16 v[98:99], v247 offset:60416
	ds_read_b64_tr_b16 v[100:101], v247 offset:60928
	ds_read_b128 v[174:177], v114 offset:4096
	ds_read_b128 v[170:173], v114 offset:4608
	s_waitcnt lgkmcnt(12)
	v_mfma_f32_32x32x16_bf16 v[50:65], v[138:141], v[102:105], v[50:65]
	v_exp_f32_e32 v70, v70
	v_exp_f32_e32 v71, v71
	ds_read_b64_tr_b16 v[102:103], v247 offset:63488
	ds_read_b64_tr_b16 v[104:105], v247 offset:64000
	ds_read_b128 v[166:169], v114 offset:6144
	ds_read_b128 v[162:165], v114 offset:6656
	s_waitcnt lgkmcnt(14)
	v_mfma_f32_32x32x16_bf16 v[50:65], v[130:133], v[106:109], v[50:65]
	v_exp_f32_e32 v72, v72
	v_exp_f32_e32 v73, v73
	ds_read_b64_tr_b16 v[106:107], v247 offset:64512
	ds_read_b64_tr_b16 v[108:109], v247 offset:65024
	s_waitcnt lgkmcnt(12)
	v_mfma_f32_32x32x16_bf16 v[34:49], v[138:141], v[110:113], v[34:49]
	v_exp_f32_e32 v74, v74
	v_exp_f32_e32 v75, v75
	s_waitcnt lgkmcnt(8)
	v_mfma_f32_32x32x16_bf16 v[34:49], v[130:133], v[98:101], v[34:49]
	v_exp_f32_e32 v76, v76
	v_exp_f32_e32 v77, v77
	s_waitcnt lgkmcnt(4)
	v_mfma_f32_32x32x16_bf16 v[2:17], v[138:141], v[102:105], v[2:17]
	v_exp_f32_e32 v78, v78
	v_exp_f32_e32 v79, v79
	s_waitcnt lgkmcnt(0)
	v_mfma_f32_32x32x16_bf16 v[2:17], v[130:133], v[106:109], v[2:17]
	v_exp_f32_e32 v80, v80
	v_exp_f32_e32 v81, v81
	s_waitcnt vmcnt(4) lgkmcnt(0)
	s_barrier
	s_andn2_b64 vcc, exec, s[36:37]
	s_cbranch_vccnz .LBB0_1315
	s_waitcnt lgkmcnt(0)
	ds_read_b128 v[98:101], v213 offset:96
	ds_read_b128 v[102:105], v213 offset:64
	ds_read_b128 v[106:109], v213 offset:32
	ds_read_b128 v[110:113], v213
	s_waitcnt lgkmcnt(3)
	v_pk_mul_f32 v[30:31], v[30:31], v[98:99]
	s_waitcnt lgkmcnt(2)
	v_pk_mul_f32 v[26:27], v[26:27], v[102:103]
	s_waitcnt lgkmcnt(1)
	v_pk_mul_f32 v[22:23], v[22:23], v[106:107]
	v_pk_mul_f32 v[32:33], v[32:33], v[100:101]
	v_pk_mul_f32 v[28:29], v[28:29], v[104:105]
	v_pk_mul_f32 v[24:25], v[24:25], v[108:109]
	s_waitcnt lgkmcnt(0)
	v_pk_mul_f32 v[20:21], v[20:21], v[112:113]
	v_pk_mul_f32 v[18:19], v[18:19], v[110:111]
	v_pk_mul_f32 v[62:63], v[62:63], v[98:99]
	v_pk_mul_f32 v[58:59], v[58:59], v[102:103]
	v_pk_mul_f32 v[54:55], v[54:55], v[106:107]
	v_pk_mul_f32 v[64:65], v[64:65], v[100:101]
	v_pk_mul_f32 v[60:61], v[60:61], v[104:105]
	v_pk_mul_f32 v[56:57], v[56:57], v[108:109]
	v_pk_mul_f32 v[52:53], v[52:53], v[112:113]
	v_pk_mul_f32 v[50:51], v[50:51], v[110:111]
	v_pk_mul_f32 v[46:47], v[46:47], v[98:99]
	v_pk_mul_f32 v[42:43], v[42:43], v[102:103]
	v_pk_mul_f32 v[38:39], v[38:39], v[106:107]
	v_pk_mul_f32 v[48:49], v[48:49], v[100:101]
	v_pk_mul_f32 v[44:45], v[44:45], v[104:105]
	v_pk_mul_f32 v[40:41], v[40:41], v[108:109]
	v_pk_mul_f32 v[36:37], v[36:37], v[112:113]
	v_pk_mul_f32 v[34:35], v[34:35], v[110:111]
	v_pk_mul_f32 v[14:15], v[14:15], v[98:99]
	v_pk_mul_f32 v[10:11], v[10:11], v[102:103]
	v_pk_mul_f32 v[6:7], v[6:7], v[106:107]
	v_pk_mul_f32 v[16:17], v[16:17], v[100:101]
	v_pk_mul_f32 v[12:13], v[12:13], v[104:105]
	v_pk_mul_f32 v[8:9], v[8:9], v[108:109]
	v_pk_mul_f32 v[4:5], v[4:5], v[112:113]
	v_pk_mul_f32 v[2:3], v[2:3], v[110:111]
.LBB0_1315:
	s_add_i32 s30, s27, 0x4000
	s_cmpk_lg_u32 s27, 0x8000
	s_cselect_b32 s40, s30, 0
	s_add_i32 s30, s28, 2
	v_lshl_add_u64 v[214:215], v[214:215], 0, s[48:49]
	s_cmp_ge_u32 s30, s26
	v_lshl_add_u64 v[216:217], v[216:217], 0, s[48:49]
	s_cbranch_scc1 Lattn_nb_exit
	s_mov_b32 s28, s30
	s_mov_b32 s30, s29
	s_mov_b32 s91, s27
	s_mov_b32 s29, s40
	s_branch .LBB0_1309
Lattn_nb_exit:
	v_lshl_add_u32 v218, v235, 4, s14
	v_add_u32_e32 v218, 0x1ca00, v218
	ds_read_b128 v[230:233], v218 offset:3072
	ds_read_b128 v[226:229], v218 offset:2048
	ds_read_b128 v[222:225], v218 offset:1024
	ds_read_b128 v[218:221], v218
	s_waitcnt lgkmcnt(0)
	s_branch .LBB0_1324
.LBB0_1317:
	v_max_f32_e32 v78, v78, v78
	v_max_f32_e32 v79, 0, v78
	v_exp_f32_e64 v78, -v79
	s_and_saveexec_b64 s[54:55], s[38:39]
	ds_write_b32 v239, v78
	s_or_b64 exec, exec, s[54:55]
	v_add_f32_e32 v243, v243, v79
	v_mul_f32_e32 v190, v190, v78
	v_sub_f32_e32 v114, v114, v79
	v_sub_f32_e32 v115, v115, v79
	v_sub_f32_e32 v116, v116, v79
	v_sub_f32_e32 v117, v117, v79
	v_sub_f32_e32 v118, v118, v79
	v_sub_f32_e32 v119, v119, v79
	v_sub_f32_e32 v120, v120, v79
	v_sub_f32_e32 v121, v121, v79
	v_sub_f32_e32 v122, v122, v79
	v_sub_f32_e32 v123, v123, v79
	v_sub_f32_e32 v124, v124, v79
	v_sub_f32_e32 v125, v125, v79
	v_sub_f32_e32 v126, v126, v79
	v_sub_f32_e32 v127, v127, v79
	v_sub_f32_e32 v128, v128, v79
	v_sub_f32_e32 v129, v129, v79
	v_sub_f32_e32 v98, v98, v79
	v_sub_f32_e32 v99, v99, v79
	v_sub_f32_e32 v100, v100, v79
	v_sub_f32_e32 v101, v101, v79
	v_sub_f32_e32 v102, v102, v79
	v_sub_f32_e32 v103, v103, v79
	v_sub_f32_e32 v104, v104, v79
	v_sub_f32_e32 v105, v105, v79
	v_sub_f32_e32 v106, v106, v79
	v_sub_f32_e32 v107, v107, v79
	v_sub_f32_e32 v108, v108, v79
	v_sub_f32_e32 v109, v109, v79
	v_sub_f32_e32 v110, v110, v79
	v_sub_f32_e32 v111, v111, v79
	v_sub_f32_e32 v112, v112, v79
	v_sub_f32_e32 v113, v113, v79
	v_sub_f32_e32 v218, v218, v79
	v_sub_f32_e32 v219, v219, v79
	v_sub_f32_e32 v220, v220, v79
	v_sub_f32_e32 v221, v221, v79
	v_sub_f32_e32 v222, v222, v79
	v_sub_f32_e32 v223, v223, v79
	v_sub_f32_e32 v224, v224, v79
	v_sub_f32_e32 v225, v225, v79
	v_sub_f32_e32 v226, v226, v79
	v_sub_f32_e32 v227, v227, v79
	v_sub_f32_e32 v228, v228, v79
	v_sub_f32_e32 v229, v229, v79
	v_sub_f32_e32 v230, v230, v79
	v_sub_f32_e32 v231, v231, v79
	v_sub_f32_e32 v232, v232, v79
	v_sub_f32_e32 v233, v233, v79
	s_branch .LBB0_1310
.LBB0_1320:
	v_max_f32_e32 v110, v110, v110
	v_max_f32_e32 v111, 0, v110
	v_exp_f32_e64 v110, -v111
	s_and_saveexec_b64 s[54:55], s[38:39]
	ds_write_b32 v239, v110
	s_or_b64 exec, exec, s[54:55]
	v_add_f32_e32 v243, v243, v111
	v_mul_f32_e32 v250, v250, v110
	v_sub_f32_e32 v82, v82, v111
	v_sub_f32_e32 v83, v83, v111
	v_sub_f32_e32 v84, v84, v111
	v_sub_f32_e32 v85, v85, v111
	v_sub_f32_e32 v86, v86, v111
	v_sub_f32_e32 v87, v87, v111
	v_sub_f32_e32 v88, v88, v111
	v_sub_f32_e32 v89, v89, v111
	v_sub_f32_e32 v90, v90, v111
	v_sub_f32_e32 v91, v91, v111
	v_sub_f32_e32 v92, v92, v111
	v_sub_f32_e32 v93, v93, v111
	v_sub_f32_e32 v94, v94, v111
	v_sub_f32_e32 v95, v95, v111
	v_sub_f32_e32 v96, v96, v111
	v_sub_f32_e32 v97, v97, v111
	v_sub_f32_e32 v66, v66, v111
	v_sub_f32_e32 v67, v67, v111
	v_sub_f32_e32 v68, v68, v111
	v_sub_f32_e32 v69, v69, v111
	v_sub_f32_e32 v70, v70, v111
	v_sub_f32_e32 v71, v71, v111
	v_sub_f32_e32 v72, v72, v111
	v_sub_f32_e32 v73, v73, v111
	v_sub_f32_e32 v74, v74, v111
	v_sub_f32_e32 v75, v75, v111
	v_sub_f32_e32 v76, v76, v111
	v_sub_f32_e32 v77, v77, v111
	v_sub_f32_e32 v78, v78, v111
	v_sub_f32_e32 v79, v79, v111
	v_sub_f32_e32 v80, v80, v111
	v_sub_f32_e32 v81, v81, v111
	v_sub_f32_e32 v218, v218, v111
	v_sub_f32_e32 v219, v219, v111
	v_sub_f32_e32 v220, v220, v111
	v_sub_f32_e32 v221, v221, v111
	v_sub_f32_e32 v222, v222, v111
	v_sub_f32_e32 v223, v223, v111
	v_sub_f32_e32 v224, v224, v111
	v_sub_f32_e32 v225, v225, v111
	v_sub_f32_e32 v226, v226, v111
	v_sub_f32_e32 v227, v227, v111
	v_sub_f32_e32 v228, v228, v111
	v_sub_f32_e32 v229, v229, v111
	v_sub_f32_e32 v230, v230, v111
	v_sub_f32_e32 v231, v231, v111
	v_sub_f32_e32 v232, v232, v111
	v_sub_f32_e32 v233, v233, v111
	s_branch .LBB0_1313
